# attention: Q/K global loads issued before the V-staging barrier instead of after it
# baseline (speedup 1.0000x reference)
; #define ATT_LOADK(buf, grp) do { _Pragma("unroll") for (int tt = 0; tt < 3; ++tt) { int ki = kbase + 16 * ((grp) * 3 + tt); ki = ki < 0 ? 0 : (ki > a.m - 1 ? a.m - 1 : ki); \
;             const bf16_t* kp = kcol + (size_t)ki * 128; \
;             _Pragma("unroll") for (int ks = 0; ks < 4; ++ks) Kf[buf][tt][ks] = *(const bf16x8*)(kp + 32 * ks); } } while (0)
; __device__ __forceinline__ void attn_phase(LAS unsigned char* lds, bf16_t* qkv, float* lse, const float* biasT, int G) {
;     ...
;         const size_t tokq = (size_t)(a.pos0 + a.r + ((16 * w4 + li) << a.dsh));
;         const int pbase = a.seq_base + a.r * a.m;
;         bf16_t* qp = qkv + ((size_t)a.head * M_TOK + pbase + a.i0 + 16 * w4 + li) * 128;
;         bf16x8 Qf[4];
; #pragma unroll
;         for (int ks = 0; ks < 4; ++ks) Qf[ks] = *(const bf16x8*)(qp + 32 * ks + 8 * lg);
;         const int kbase = a.i0 - 64 + 16 * w4 + li;
;         const bf16_t* kcol = qkv + ((size_t)(12 + a.head) * M_TOK + pbase) * 128 + 8 * lg;
;         f32x4 sa[10];
;         bf16x8 Kf[2][3][4];
;     ...
;         ATT_LOADK(0, 0); ATT_LOADK(1, 1);
.LBB0_425:
	s_or_b64 exec, exec, s[0:1]
	s_mul_i32 s0, s10, 0xfffffd00
	s_add_i32 s0, s0, s9
	s_lshl_b32 s1, s0, 6
	s_and_b32 s9, s1, 0xffffe000
	s_cmpk_lt_i32 s0, 0x200
	s_cselect_b32 s0, 13, 14
	s_cselect_b32 s9, s9, 0x8000
	s_ashr_i32 s11, s10, 1
	s_and_b32 s12, s11, -2
	s_sub_i32 s11, s0, s12
	s_sub_i32 s30, s1, s9
	s_ashr_i32 s96, s30, s11
	s_lshl_b32 s31, s96, s11
	s_sub_i32 s13, s30, s31
	s_add_i32 s16, s31, s9
	s_mul_hi_i32 s0, s10, 0xc000
	s_ashr_i32 s18, s16, 31
	s_ashr_i32 s1, s13, 31
	s_mul_i32 s17, s10, 0xc000
	v_mov_b32_e32 v3, s0
	s_add_u32 s0, s13, s16
	v_or_b32_e32 v2, s17, v184
	s_addc_u32 s1, s1, s18
	v_lshl_add_u64 v[2:3], s[0:1], 0, v[2:3]
	v_readlane_b32 s0, v250, 21
	s_add_i32 s15, s13, s0
	s_add_i32 s0, s10, 12
	s_add_i32 s17, s17, 0x90000
	v_lshlrev_b64 v[2:3], 8, v[2:3]
	s_mul_hi_i32 s1, s0, 0xc000
	s_add_u32 s0, s17, s16
	v_lshl_add_u64 v[194:195], s[92:93], 0, v[2:3]
	v_mov_b32_e32 v191, v1
	s_addc_u32 s1, s1, s18
	v_lshl_add_u64 v[2:3], v[194:195], 0, v[190:191]
	s_lshl_b64 s[0:1], s[0:1], 8
	global_load_dwordx4 v[96:99], v[2:3], off
	global_load_dwordx4 v[92:95], v[2:3], off offset:64
	global_load_dwordx4 v[88:91], v[2:3], off offset:128
	global_load_dwordx4 v[52:55], v[2:3], off offset:192
	v_add_u32_e32 v0, s15, v216
	v_lshl_add_u64 v[2:3], v[186:187], 0, s[0:1]
	s_bfm_b32 s0, s11, 0
	v_min_i32_e32 v56, s0, v0
	v_ashrrev_i32_e32 v57, 31, v56
	v_lshlrev_b64 v[56:57], 7, v[56:57]
	v_cmp_lt_i32_e32 vcc, -1, v0
	s_movk_i32 s1, 0xffef
	v_add_u32_e32 v58, 48, v0
	v_cndmask_b32_e32 v57, 0, v57, vcc
	v_cndmask_b32_e32 v56, 0, v56, vcc
	v_lshl_add_u64 v[56:57], v[56:57], 1, v[2:3]
	global_load_dwordx4 v[68:71], v[56:57], off
	global_load_dwordx4 v[72:75], v[56:57], off offset:64
	global_load_dwordx4 v[80:83], v[56:57], off offset:128
	global_load_dwordx4 v[84:87], v[56:57], off offset:192
	v_add_u32_e32 v56, 16, v0
	v_min_i32_e32 v56, s0, v56
	v_ashrrev_i32_e32 v57, 31, v56
	v_lshlrev_b64 v[56:57], 7, v[56:57]
	v_cmp_lt_i32_e32 vcc, s1, v0
	s_movk_i32 s1, 0xffdf
	v_add_u32_e32 v102, 64, v0
	v_cndmask_b32_e32 v57, 0, v57, vcc
	v_cndmask_b32_e32 v56, 0, v56, vcc
	v_lshl_add_u64 v[56:57], v[56:57], 1, v[2:3]
	global_load_dwordx4 v[116:119], v[56:57], off
	global_load_dwordx4 v[136:139], v[56:57], off offset:64
	global_load_dwordx4 v[140:143], v[56:57], off offset:128
	global_load_dwordx4 v[144:147], v[56:57], off offset:192
	v_add_u32_e32 v56, 32, v0
	v_min_i32_e32 v56, s0, v56
	v_ashrrev_i32_e32 v57, 31, v56
	v_lshlrev_b64 v[56:57], 7, v[56:57]
	v_cmp_lt_i32_e32 vcc, s1, v0
	v_min_i32_e32 v100, s0, v102
	v_add_u32_e32 v122, 0x50, v0
	v_cndmask_b32_e32 v57, 0, v57, vcc
	v_cndmask_b32_e32 v56, 0, v56, vcc
	v_lshl_add_u64 v[56:57], v[56:57], 1, v[2:3]
	global_load_dwordx4 v[148:151], v[56:57], off
	global_load_dwordx4 v[152:155], v[56:57], off offset:64
	global_load_dwordx4 v[156:159], v[56:57], off offset:128
	global_load_dwordx4 v[160:163], v[56:57], off offset:192
	v_min_i32_e32 v56, s0, v58
	v_ashrrev_i32_e32 v57, 31, v56
	v_lshlrev_b64 v[56:57], 7, v[56:57]
	v_cmp_lt_i32_e32 vcc, -1, v58
	v_ashrrev_i32_e32 v101, 31, v100
	v_min_i32_e32 v120, s0, v122
	v_cndmask_b32_e32 v57, 0, v57, vcc
	v_cndmask_b32_e32 v56, 0, v56, vcc
	v_lshlrev_b64 v[100:101], 7, v[100:101]
	v_cmp_lt_i32_e32 vcc, -1, v102
	v_ashrrev_i32_e32 v121, 31, v120
	v_lshlrev_b64 v[120:121], 7, v[120:121]
	v_cndmask_b32_e32 v101, 0, v101, vcc
	v_cndmask_b32_e32 v100, 0, v100, vcc
	v_cmp_lt_i32_e32 vcc, -1, v122
	v_lshl_add_u64 v[76:77], v[56:57], 1, v[2:3]
	v_lshl_add_u64 v[112:113], v[100:101], 1, v[2:3]
	v_cndmask_b32_e32 v121, 0, v121, vcc
	v_cndmask_b32_e32 v120, 0, v120, vcc
	v_lshl_add_u64 v[132:133], v[120:121], 1, v[2:3]
	global_load_dwordx4 v[56:59], v[76:77], off
	global_load_dwordx4 v[60:63], v[76:77], off offset:64
	global_load_dwordx4 v[64:67], v[76:77], off offset:128
	s_nop 0
	global_load_dwordx4 v[76:79], v[76:77], off offset:192
	s_nop 0
	global_load_dwordx4 v[100:103], v[112:113], off
	global_load_dwordx4 v[104:107], v[112:113], off offset:64
	global_load_dwordx4 v[108:111], v[112:113], off offset:128
	s_nop 0
	global_load_dwordx4 v[112:115], v[112:113], off offset:192
	s_nop 0
	global_load_dwordx4 v[120:123], v[132:133], off
	global_load_dwordx4 v[124:127], v[132:133], off offset:64
	global_load_dwordx4 v[128:131], v[132:133], off offset:128
	s_nop 0
	global_load_dwordx4 v[132:135], v[132:133], off offset:192
	s_waitcnt lgkmcnt(0)
	s_barrier
; #define ATT_LOADK(buf, grp) do { _Pragma("unroll") for (int tt = 0; tt < 3; ++tt) { int ki = kbase + 16 * ((grp) * 3 + tt); ki = ki < 0 ? 0 : (ki > a.m - 1 ? a.m - 1 : ki); \
;             const bf16_t* kp = kcol + (size_t)ki * 128; \
;             _Pragma("unroll") for (int ks = 0; ks < 4; ++ks) Kf[buf][tt][ks] = *(const bf16x8*)(kp + 32 * ks); } } while (0)
; #define ATT_MMAK(buf, grp) do { _Pragma("unroll") for (int tt = 0; tt < 3; ++tt) { f32x4 acc_ = (f32x4){0.f, 0.f, 0.f, 0.f}; \
;             _Pragma("unroll") for (int ks = 0; ks < 4; ++ks) acc_ = __builtin_amdgcn_mfma_f32_16x16x32_bf16(Kf[buf][tt][ks], Qf[ks], acc_, 0, 0, 0); sa[(grp) * 3 + tt] = acc_; } } while (0)
; __device__ __forceinline__ void attn_phase(LAS unsigned char* lds, bf16_t* qkv, float* lse, const float* biasT, int G) {
;     ...
;         ATT_LOADK(0, 0); ATT_LOADK(1, 1);
;         __builtin_amdgcn_sched_barrier(0);
;         ATT_MMAK(0, 0);
;         __builtin_amdgcn_sched_barrier(0);
;         ATT_LOADK(0, 2);
;         if (pairn < 4608) { const AttnItem an = attn_item(pairn * 2 + half); attn_load_v(an, qkv, ht, vreg); }
	s_waitcnt vmcnt(23)
	v_mfma_f32_16x16x32_bf16 v[68:71], v[68:71], v[96:99], 0
	s_waitcnt vmcnt(22)
	v_mfma_f32_16x16x32_bf16 v[68:71], v[72:75], v[92:95], v[68:71]
	s_waitcnt vmcnt(21)
	v_mfma_f32_16x16x32_bf16 v[68:71], v[80:83], v[88:91], v[68:71]
	s_waitcnt vmcnt(20)
	v_mfma_f32_16x16x32_bf16 v[84:87], v[84:87], v[52:55], v[68:71]
	s_waitcnt vmcnt(19)
	v_mfma_f32_16x16x32_bf16 v[68:71], v[116:119], v[96:99], 0
	s_waitcnt vmcnt(18)
	v_mfma_f32_16x16x32_bf16 v[68:71], v[136:139], v[92:95], v[68:71]
	s_waitcnt vmcnt(17)
	v_mfma_f32_16x16x32_bf16 v[68:71], v[140:143], v[88:91], v[68:71]
	s_waitcnt vmcnt(16)
	v_mfma_f32_16x16x32_bf16 v[72:75], v[144:147], v[52:55], v[68:71]
	s_waitcnt vmcnt(15)
	v_mfma_f32_16x16x32_bf16 v[68:71], v[148:151], v[96:99], 0
	s_waitcnt vmcnt(14)
	v_mfma_f32_16x16x32_bf16 v[68:71], v[152:155], v[92:95], v[68:71]
	s_waitcnt vmcnt(13)
	v_mfma_f32_16x16x32_bf16 v[68:71], v[156:159], v[88:91], v[68:71]
	s_waitcnt vmcnt(12)
	v_mfma_f32_16x16x32_bf16 v[68:71], v[160:163], v[52:55], v[68:71]
	v_add_u32_e32 v82, 0x60, v0
	v_min_i32_e32 v80, s0, v82
	v_ashrrev_i32_e32 v81, 31, v80
	v_lshlrev_b64 v[80:81], 7, v[80:81]
	v_cmp_lt_i32_e32 vcc, -1, v82
	v_add_u32_e32 v82, 0x70, v0
	v_add_u32_e32 v0, 0x80, v0
	v_cndmask_b32_e32 v81, 0, v81, vcc
	v_cndmask_b32_e32 v80, 0, v80, vcc
	v_lshl_add_u64 v[80:81], v[80:81], 1, v[2:3]
	global_load_dwordx4 v[136:139], v[80:81], off
	global_load_dwordx4 v[140:143], v[80:81], off offset:64
	global_load_dwordx4 v[144:147], v[80:81], off offset:128
	global_load_dwordx4 v[148:151], v[80:81], off offset:192
	v_min_i32_e32 v80, s0, v82
	v_ashrrev_i32_e32 v81, 31, v80
	v_lshlrev_b64 v[80:81], 7, v[80:81]
	v_cmp_lt_i32_e32 vcc, -1, v82
	s_cmpk_gt_i32 s14, 0x11ff
	s_nop 0
	v_cndmask_b32_e32 v81, 0, v81, vcc
	v_cndmask_b32_e32 v80, 0, v80, vcc
	v_lshl_add_u64 v[80:81], v[80:81], 1, v[2:3]
	global_load_dwordx4 v[152:155], v[80:81], off
	global_load_dwordx4 v[156:159], v[80:81], off offset:64
	global_load_dwordx4 v[160:163], v[80:81], off offset:128
	global_load_dwordx4 v[164:167], v[80:81], off offset:192
	v_min_i32_e32 v80, s0, v0
	v_ashrrev_i32_e32 v81, 31, v80
	v_lshlrev_b64 v[80:81], 7, v[80:81]
	v_cmp_lt_i32_e32 vcc, -1, v0
	s_nop 1
	v_cndmask_b32_e32 v81, 0, v81, vcc
	v_cndmask_b32_e32 v80, 0, v80, vcc
	v_lshl_add_u64 v[2:3], v[80:81], 1, v[2:3]
	global_load_dwordx4 v[176:179], v[2:3], off
	global_load_dwordx4 v[172:175], v[2:3], off offset:64
	global_load_dwordx4 v[168:171], v[2:3], off offset:128
	global_load_dwordx4 v[116:119], v[2:3], off offset:192
	s_cbranch_scc1 .LBB0_451
	s_lshl_b32 s0, s14, 1
	s_add_i32 s0, s0, s94
	s_mul_hi_i32 s1, s0, 0x2aaaaaab
	s_lshr_b32 s14, s1, 31
	s_ashr_i32 s1, s1, 7
	s_add_i32 s14, s1, s14
	s_mul_i32 s1, s14, 0xfffffd00
	s_add_i32 s1, s1, s0
	s_lshl_b32 s0, s1, 6
	s_and_b32 s16, s0, 0xffffe000
	s_cmpk_lt_i32 s1, 0x200
	s_cselect_b32 s1, 13, 14
	s_cselect_b32 s16, s16, 0x8000
	s_ashr_i32 s17, s14, 1
	s_and_b32 s17, s17, -2
	s_sub_i32 s1, s1, s17
	s_lshl_b32 s18, 1, s1
	s_sub_i32 s0, s0, s16
	s_lshl_b32 s1, -1, s1
	s_and_b32 s17, s1, s0
	s_sub_i32 s19, s0, s17
	v_add_u32_e32 v0, s19, v220
	v_mov_b32_e32 v6, v1
	v_mov_b32_e32 v7, v1
	v_cmp_lt_i32_e32 vcc, -1, v0
	v_cmp_gt_i32_e64 s[0:1], s18, v0
	v_mov_b32_e32 v4, v1
	v_mov_b32_e32 v5, v1
	v_mov_b64_e32 v[10:11], v[6:7]
	s_and_b64 s[28:29], vcc, s[0:1]
	v_mov_b64_e32 v[8:9], v[4:5]
	s_and_saveexec_b64 s[0:1], s[28:29]
	s_cbranch_execz .LBB0_428
	s_add_i32 s28, s14, 24
	s_mul_hi_i32 s29, s28, 0xc000
	s_mul_i32 s28, s28, 0xc000
	s_ashr_i32 vcc_lo, s16, 31
	s_ashr_i32 vcc_hi, s17, 31
	s_add_u32 s28, s28, s16
	s_addc_u32 s29, s29, vcc_lo
	s_add_u32 s28, s28, s17
	s_addc_u32 s29, s29, vcc_hi
	v_lshl_add_u64 v[2:3], s[28:29], 0, v[0:1]
	v_lshlrev_b64 v[2:3], 8, v[2:3]
	v_lshl_add_u64 v[2:3], v[188:189], 0, v[2:3]
	global_load_dwordx4 v[8:11], v[2:3], off
